# speedup vs baseline: 1.0168x; 1.0020x over previous
; __device__ __forceinline__ int otid() { int t = threadIdx.x; asm volatile("" : "+v"(t)); return t; }
; __device__ __forceinline__ int obid() { int t = blockIdx.x; asm volatile("" : "+s"(t)); return t; }
; __device__ __forceinline__ void prep_s5(const PRef& P, int slot, bfr* __restrict__ Gall, bfr* __restrict__ W2all, float2* __restrict__ lam16) {
;   float2* pw = (float2*)g_lds;
;   float2* bb = pw + 2 * 17 * 64;
;   float2* cc = bb + 2 * 64 * 16;
;   float* kt = (float*)(cc + 2 * 16 * 64);
;   const int tid = otid();
;   for (int g = obid(); g < 64; g += gridDim.x) {
;     __syncthreads();
;     if (tid < 128) {
;       const int dir = tid >> 6, p = tid & 63; const long sg = ((long)(slot * 2 + dir)) * 64 + g;
;       const float lr = P.in(9)[sg * 64 + p], li = P.in(10)[sg * 64 + p]; const float stepf = expf(P.in(11)[sg]);
.LBB0_146:
	s_addk_i32 s14, 0xb0
	s_ashr_i32 s71, s14, 31
	s_abs_i32 s72, s14
	v_mov_b32_e32 v114, v182
	s_mov_b32 s28, s94
	s_mov_b32 s32, 0
	s_mov_b32 s95, 0xfdff
	s_mov_b32 s90, 0
	s_mov_b32 s91, 0x1fdff
	s_cmpk_lg_u32 s96, 0x100
	s_cbranch_scc1 .Lps5a_nosplit
	s_and_b32 s28, s94, 63
	s_lshr_b32 s32, s94, 6
	s_lshl_b32 s90, s32, 15
	s_lshl_b32 s32, s32, 14
	s_add_u32 s95, s32, 0x3dff
	s_add_u32 s91, s90, 0x7dff
.Lps5a_nosplit:
	s_barrier
	s_cmp_gt_i32 s28, 63
	s_cbranch_scc1 .LBB0_362
	v_ashrrev_i32_e32 v4, 6, v114
	v_ashrrev_i32_e32 v5, 31, v4
	s_movk_i32 s8, 0x2200
	v_ashrrev_i32_e32 v6, 8, v114
	v_lshlrev_b64 v[116:117], 6, v[4:5]
	v_mul_lo_u32 v8, v4, s8
	v_bfe_u32 v4, v114, 4, 4
	v_mul_i32_i24_e32 v7, 17, v6
	v_add_lshl_u32 v128, v7, v4, 9
	v_lshlrev_b32_e32 v4, 10, v4
	v_lshl_or_b32 v9, v6, 14, v4
	v_and_b32_e32 v4, 0x1ff, v114
	s_movk_i32 s15, 0x100
	s_movk_i32 s14, 0x80
	v_subrev_co_u32_e32 v4, vcc, s15, v4
	v_cmp_gt_i32_e64 s[6:7], s14, v114
	v_lshrrev_b32_e32 v7, 7, v4
	v_cmp_gt_u32_e64 s[14:15], s14, v4
	v_max_i32_e32 v4, 0x600, v114
	v_and_b32_e32 v2, 63, v114
	v_sub_u32_e32 v4, v4, v114
	v_lshlrev_b32_e32 v3, 3, v2
	v_add_u32_e32 v4, 0x1ff, v4
	v_lshl_or_b32 v129, v7, 13, v3
	v_lshl_add_u32 v130, v7, 4, v7
	v_lshrrev_b32_e32 v7, 9, v4
	v_add_u32_e32 v11, 1, v7
	v_add_u32_e32 v7, -1, v7
	v_and_b32_e32 v127, 15, v114
	v_lshrrev_b32_e32 v12, 1, v7
	v_cmp_lt_u32_e64 s[18:19], 1, v7
	v_and_b32_e32 v7, 2, v7
	v_lshlrev_b32_e32 v6, 13, v6
	v_writelane_b32 v254, s36, 4
	v_cmp_eq_u32_e64 s[20:21], 0, v7
	v_lshl_or_b32 v7, v127, 9, v6
	v_writelane_b32 v254, s37, 5
	v_add_u32_e32 v136, 0x8400, v7
	v_add_u32_e32 v137, 0x4400, v6
	v_ashrrev_i32_e32 v7, 31, v114
	v_mov_b32_e32 v6, v114
	v_writelane_b32 v254, s38, 6
	v_lshl_add_u64 v[6:7], v[6:7], 1, s[2:3]
	s_mov_b64 s[24:25], 0x1680000
	s_mov_b64 s[92:93], s[54:55]
	v_writelane_b32 v254, s39, 7
	s_add_u32 s30, s2, 0x1d800000
	s_movk_i32 s8, 0x800
	v_lshlrev_b32_e32 v10, 6, v127
	s_mov_b32 s10, 0x10000
	s_mov_b32 s12, 0x20000
	s_movk_i32 s16, 0x1ff
	v_add_u32_e32 v12, 1, v12
	v_and_b32_e32 v13, 0xfffffe, v11
	v_lshlrev_b32_e32 v134, 3, v114
	v_lshl_add_u64 v[118:119], v[6:7], 0, s[24:25]
	s_mov_b64 s[24:25], 0x1e80000
	s_mov_b32 s36, 0x6dc9c883
	s_mov_b32 s38, 0x54442d18
	s_mov_b32 s40, 0x33145c07
	s_mov_b32 s42, 0xbab60b61
	s_mov_b32 s44, 0x3d2aaaab
	s_mov_b32 s46, -0.5
	s_mov_b32 s48, 0
	s_mov_b32 s50, 0
	s_mov_b32 s52, 0
	s_mov_b32 s54, 0
	s_mov_b32 s56, 0
	s_mov_b64 s[88:89], s[60:61]
	s_addc_u32 s31, s3, 0
	v_and_b32_e32 v5, 0xffffffc0, v114
	v_lshlrev_b32_e32 v126, 7, v114
	v_cmp_gt_i32_e64 s[8:9], s8, v114
	v_cmp_gt_i32_e64 s[10:11], s10, v114
	v_cmp_gt_i32_e64 s[12:13], s12, v114
	s_xor_b64 s[34:35], vcc, -1
	v_bfe_u32 v131, v114, 4, 5
	v_cmp_lt_u32_e64 s[16:17], s16, v4
	v_lshl_add_u32 v132, v13, 9, v114
	v_mov_b32_e32 v4, v2
	v_add_u32_e32 v115, 0x200, v114
	v_and_b32_e32 v133, -2, v12
	v_cmp_ne_u32_e64 s[22:23], v11, v13
	v_add_u32_e32 v135, 0x8400, v134
	v_lshl_add_u64 v[120:121], v[6:7], 0, s[24:25]
	s_mov_b32 s73, 0x3fb8aa3b
	s_mov_b32 s74, 0xc2ce8ed0
	s_mov_b32 s75, 0x42b17218
	s_mov_b32 s37, 0x3fe45f30
	s_mov_b32 s39, 0xbff921fb
	s_mov_b32 s41, 0xbc91a626
	v_mov_b32_e32 v138, 0x37d00d01
	v_mov_b32_e32 v123, 0x3638ef1d
	s_mov_b32 s43, 0xb9500d01
	s_mov_b32 s45, 0x3c088888
	s_mov_b32 s47, 0xbe2aaaab
	v_mov_b32_e32 v124, 1.0
	v_add_u32_e32 v139, v3, v8
	s_mov_b32 s49, 0x40260000
	s_mov_b32 s51, 0x40280000
	s_mov_b32 s53, 0x402a0000
	s_mov_b32 s55, 0x402c0000
	s_mov_b32 s57, 0x402e0000
	v_mov_b32_e32 v140, 0x3ab69700
	s_mov_b32 s76, 0x43000000
	s_mov_b32 s77, 0x42b17217
	s_mov_b32 s78, 0xc1880000
	s_movk_i32 s79, 0x5ff
	v_add_u32_e32 v141, v9, v10
	s_mov_b32 s80, 0x8000
	s_mov_b64 s[58:59], 0x400
	s_mov_b32 s81, 0xfdff
	s_mov_b32 s82, 0x1fdff
	v_mov_b32_e32 v142, 0x7f800000
	v_mov_b32_e32 v143, 0x7f000000
	s_branch .LBB0_149

; __device__ __forceinline__ void prep_s5(const PRef& P, int slot, bfr* __restrict__ Gall, bfr* __restrict__ W2all, float2* __restrict__ lam16) {
;     ...
;       for (int p = 0; p < 64; ++p) { float2 c = cc[(dir * 16 + o) * 64 + p], w = pw[(dir * 17 + j) * 64 + p];
;         float xr = c.x * w.x - c.y * w.y, xi = c.x * w.y + c.y * w.x;
; #pragma unroll
;         for (int i = 0; i < 16; ++i) { float2 b = bb[(dir * 64 + p) * 16 + i]; a16[i] += xr * b.x - xi * b.y; } }
.LBB0_346:
	v_add_u32_e32 v125, s24, v136
	ds_read_b128 v[22:25], v122
	ds_read_b128 v[26:29], v122 offset:16
	ds_read_b128 v[30:33], v122 offset:32
	ds_read_b128 v[34:37], v122 offset:48
	ds_read_b128 v[38:41], v122 offset:64
	ds_read_b128 v[42:45], v122 offset:80
	ds_read_b128 v[46:49], v122 offset:96
	ds_read_b128 v[50:53], v122 offset:112
	ds_read_b128 v[54:57], v122 offset:128
	ds_read_b128 v[58:61], v122 offset:144
	ds_read_b128 v[62:65], v122 offset:160
	ds_read_b128 v[66:69], v122 offset:176
	ds_read_b128 v[70:73], v122 offset:192
	ds_read_b128 v[74:77], v122 offset:208
	ds_read_b128 v[78:81], v122 offset:224
	ds_read_b128 v[82:85], v122 offset:240
	ds_read_b128 v[86:89], v122 offset:256
	ds_read_b128 v[90:93], v122 offset:272
	ds_read_b128 v[94:97], v122 offset:288
	ds_read_b128 v[98:101], v122 offset:304
	ds_read_b128 v[102:105], v122 offset:320
	ds_read_b128 v[106:109], v122 offset:336
	ds_read_b128 v[110:113], v122 offset:352
	ds_read_b128 v[144:147], v122 offset:368
	ds_read_b128 v[148:151], v122 offset:384
	ds_read_b128 v[152:155], v122 offset:400
	ds_read_b128 v[156:159], v122 offset:416
	ds_read_b128 v[160:163], v122 offset:432
	ds_read_b128 v[164:167], v122 offset:448
	ds_read_b128 v[168:171], v122 offset:464
	ds_read_b128 v[172:175], v122 offset:480
	ds_read_b128 v[176:179], v122 offset:496
	v_add_u32_e32 v180, s24, v128
	ds_read_b128 v[184:187], v125
	ds_read_b128 v[188:191], v125 offset:16
	ds_read_b128 v[192:195], v180
	ds_read_b128 v[196:199], v180 offset:16
	s_waitcnt lgkmcnt(14)
	v_mov_b32_e32 v180, v22
	v_mov_b32_e32 v181, v24
	v_mov_b32_e32 v24, v23
	v_mov_b32_e32 v22, v26
	v_mov_b32_e32 v23, v28
	v_mov_b32_e32 v28, v27
	v_mov_b32_e32 v26, v30
	v_mov_b32_e32 v27, v32
	v_mov_b32_e32 v32, v31
	v_mov_b32_e32 v30, v34
	v_mov_b32_e32 v31, v36
	v_mov_b32_e32 v36, v35
	v_mov_b32_e32 v34, v38
	v_mov_b32_e32 v35, v40
	v_mov_b32_e32 v40, v39
	v_mov_b32_e32 v38, v42
	v_mov_b32_e32 v39, v44
	v_mov_b32_e32 v44, v43
	v_mov_b32_e32 v42, v46
	v_mov_b32_e32 v43, v48
	v_mov_b32_e32 v48, v47
	v_mov_b32_e32 v46, v50
	v_mov_b32_e32 v47, v52
	v_mov_b32_e32 v52, v51
	v_mov_b32_e32 v50, v54
	v_mov_b32_e32 v51, v56
	v_mov_b32_e32 v56, v55
	v_mov_b32_e32 v54, v58
	v_mov_b32_e32 v55, v60
	v_mov_b32_e32 v60, v59
	v_mov_b32_e32 v58, v62
	v_mov_b32_e32 v59, v64
	v_mov_b32_e32 v64, v63
	v_mov_b32_e32 v62, v66
	v_mov_b32_e32 v63, v68
	v_mov_b32_e32 v68, v67
	v_mov_b32_e32 v66, v70
	v_mov_b32_e32 v67, v72
	v_mov_b32_e32 v72, v71
	v_mov_b32_e32 v70, v74
	v_mov_b32_e32 v71, v76
	v_mov_b32_e32 v76, v75
	v_mov_b32_e32 v74, v78
	v_mov_b32_e32 v75, v80
	v_mov_b32_e32 v80, v79
	v_mov_b32_e32 v78, v82
	v_mov_b32_e32 v79, v84
	v_mov_b32_e32 v84, v83
	v_mov_b32_e32 v82, v86
	v_mov_b32_e32 v83, v88
	v_mov_b32_e32 v88, v87
	v_mov_b32_e32 v86, v90
	v_mov_b32_e32 v87, v92
	v_mov_b32_e32 v92, v91
	v_mov_b32_e32 v90, v94
	v_mov_b32_e32 v91, v96
	v_mov_b32_e32 v96, v95
	v_mov_b32_e32 v94, v98
	v_mov_b32_e32 v95, v100
	v_mov_b32_e32 v100, v99
	v_mov_b32_e32 v98, v102
	v_mov_b32_e32 v99, v104
	v_mov_b32_e32 v104, v103
	v_mov_b32_e32 v102, v106
	v_mov_b32_e32 v103, v108
	v_mov_b32_e32 v108, v107
	s_waitcnt lgkmcnt(13)
	v_mov_b32_e32 v106, v110
	v_mov_b32_e32 v107, v112
	v_mov_b32_e32 v112, v111
	s_waitcnt lgkmcnt(12)
	v_mov_b32_e32 v110, v144
	v_mov_b32_e32 v111, v146
	v_mov_b32_e32 v146, v145
	s_waitcnt lgkmcnt(11)
	v_mov_b32_e32 v144, v148
	v_mov_b32_e32 v145, v150
	v_mov_b32_e32 v150, v149
	s_waitcnt lgkmcnt(10)
	v_mov_b32_e32 v148, v152
	v_mov_b32_e32 v149, v154
	v_mov_b32_e32 v154, v153
	s_waitcnt lgkmcnt(9)
	v_mov_b32_e32 v152, v156
	v_mov_b32_e32 v153, v158
	v_mov_b32_e32 v158, v157
	s_waitcnt lgkmcnt(8)
	v_mov_b32_e32 v156, v160
	v_mov_b32_e32 v157, v162
	v_mov_b32_e32 v162, v161
	s_waitcnt lgkmcnt(7)
	v_mov_b32_e32 v160, v164
	v_mov_b32_e32 v161, v166
	v_mov_b32_e32 v166, v165
	s_waitcnt lgkmcnt(6)
	v_mov_b32_e32 v164, v168
	v_mov_b32_e32 v165, v170
	v_mov_b32_e32 v170, v169
	s_waitcnt lgkmcnt(5)
	v_mov_b32_e32 v168, v172
	v_mov_b32_e32 v169, v174
	v_mov_b32_e32 v174, v173
	s_waitcnt lgkmcnt(4)
	v_mov_b32_e32 v172, v176
	v_mov_b32_e32 v173, v178
	v_mov_b32_e32 v178, v177
	s_waitcnt lgkmcnt(1)
	v_pk_mul_f32 v[176:177], v[184:185], v[192:193]
	v_pk_mul_f32 v[184:185], v[184:185], v[192:193] op_sel:[1,0] op_sel_hi:[0,1]
	v_pk_mul_f32 v[192:193], v[186:187], v[194:195]
	v_pk_mul_f32 v[186:187], v[186:187], v[194:195] op_sel:[1,0] op_sel_hi:[0,1]
	v_pk_add_f32 v[184:185], v[184:185], v[184:185] op_sel:[0,1] op_sel_hi:[0,1]
	s_waitcnt lgkmcnt(0)
; __device__ __forceinline__ void prep_s5(const PRef& P, int slot, bfr* __restrict__ Gall, bfr* __restrict__ W2all, float2* __restrict__ lam16) {
;     ...
;       for (int p = 0; p < 64; ++p) { float2 c = cc[(dir * 16 + o) * 64 + p], w = pw[(dir * 17 + j) * 64 + p];
;         float xr = c.x * w.x - c.y * w.y, xi = c.x * w.y + c.y * w.x;
; #pragma unroll
;         for (int i = 0; i < 16; ++i) { float2 b = bb[(dir * 64 + p) * 16 + i]; a16[i] += xr * b.x - xi * b.y; } }
	v_pk_mul_f32 v[194:195], v[188:189], v[196:197]
	v_pk_mul_f32 v[188:189], v[188:189], v[196:197] op_sel:[1,0] op_sel_hi:[0,1]
	v_pk_add_f32 v[176:177], v[176:177], v[176:177] op_sel:[0,1] op_sel_hi:[0,1] neg_lo:[0,1] neg_hi:[0,1]
	v_pk_add_f32 v[186:187], v[186:187], v[186:187] op_sel:[0,1] op_sel_hi:[0,1]
	v_pk_mul_f32 v[24:25], v[184:185], v[24:25]
	v_pk_mul_f32 v[28:29], v[184:185], v[28:29]
	v_pk_mul_f32 v[32:33], v[184:185], v[32:33]
	v_pk_mul_f32 v[36:37], v[184:185], v[36:37]
	v_pk_mul_f32 v[40:41], v[184:185], v[40:41]
	v_pk_mul_f32 v[44:45], v[184:185], v[44:45]
	v_pk_mul_f32 v[48:49], v[184:185], v[48:49]
	v_pk_mul_f32 v[52:53], v[184:185], v[52:53]
	v_pk_mul_f32 v[196:197], v[190:191], v[198:199]
	v_pk_mul_f32 v[190:191], v[190:191], v[198:199] op_sel:[1,0] op_sel_hi:[0,1]
	v_pk_add_f32 v[192:193], v[192:193], v[192:193] op_sel:[0,1] op_sel_hi:[0,1] neg_lo:[0,1] neg_hi:[0,1]
	v_pk_add_f32 v[188:189], v[188:189], v[188:189] op_sel:[0,1] op_sel_hi:[0,1]
	v_pk_mul_f32 v[56:57], v[186:187], v[56:57]
	v_pk_mul_f32 v[60:61], v[186:187], v[60:61]
	v_pk_mul_f32 v[64:65], v[186:187], v[64:65]
	v_pk_mul_f32 v[68:69], v[186:187], v[68:69]
	v_pk_mul_f32 v[72:73], v[186:187], v[72:73]
	v_pk_mul_f32 v[76:77], v[186:187], v[76:77]
	v_pk_mul_f32 v[80:81], v[186:187], v[80:81]
	v_pk_mul_f32 v[84:85], v[186:187], v[84:85]
	v_pk_fma_f32 v[24:25], v[180:181], v[176:177], v[24:25] neg_lo:[0,0,1] neg_hi:[0,0,1]
	v_pk_fma_f32 v[22:23], v[176:177], v[22:23], v[28:29] neg_lo:[0,0,1] neg_hi:[0,0,1]
	v_pk_fma_f32 v[26:27], v[176:177], v[26:27], v[32:33] neg_lo:[0,0,1] neg_hi:[0,0,1]
	v_pk_fma_f32 v[28:29], v[176:177], v[30:31], v[36:37] neg_lo:[0,0,1] neg_hi:[0,0,1]
	v_pk_fma_f32 v[30:31], v[176:177], v[34:35], v[40:41] neg_lo:[0,0,1] neg_hi:[0,0,1]
	v_pk_fma_f32 v[32:33], v[176:177], v[38:39], v[44:45] neg_lo:[0,0,1] neg_hi:[0,0,1]
	v_pk_fma_f32 v[34:35], v[176:177], v[42:43], v[48:49] neg_lo:[0,0,1] neg_hi:[0,0,1]
	v_pk_fma_f32 v[36:37], v[176:177], v[46:47], v[52:53] neg_lo:[0,0,1] neg_hi:[0,0,1]
	v_pk_add_f32 v[194:195], v[194:195], v[194:195] op_sel:[0,1] op_sel_hi:[0,1] neg_lo:[0,1] neg_hi:[0,1]
	v_pk_add_f32 v[190:191], v[190:191], v[190:191] op_sel:[0,1] op_sel_hi:[0,1]
	v_pk_mul_f32 v[88:89], v[188:189], v[88:89]
	v_pk_mul_f32 v[92:93], v[188:189], v[92:93]
	v_pk_mul_f32 v[96:97], v[188:189], v[96:97]
	v_pk_mul_f32 v[100:101], v[188:189], v[100:101]
	v_pk_mul_f32 v[104:105], v[188:189], v[104:105]
	v_pk_mul_f32 v[108:109], v[188:189], v[108:109]
	v_pk_mul_f32 v[112:113], v[188:189], v[112:113]
	v_pk_mul_f32 v[146:147], v[188:189], v[146:147]
	v_pk_fma_f32 v[38:39], v[50:51], v[192:193], v[56:57] neg_lo:[0,0,1] neg_hi:[0,0,1]
	v_pk_fma_f32 v[40:41], v[192:193], v[54:55], v[60:61] neg_lo:[0,0,1] neg_hi:[0,0,1]
	v_pk_fma_f32 v[42:43], v[192:193], v[58:59], v[64:65] neg_lo:[0,0,1] neg_hi:[0,0,1]
	v_pk_fma_f32 v[44:45], v[192:193], v[62:63], v[68:69] neg_lo:[0,0,1] neg_hi:[0,0,1]
	v_pk_fma_f32 v[46:47], v[192:193], v[66:67], v[72:73] neg_lo:[0,0,1] neg_hi:[0,0,1]
	v_pk_fma_f32 v[48:49], v[192:193], v[70:71], v[76:77] neg_lo:[0,0,1] neg_hi:[0,0,1]
	v_pk_fma_f32 v[50:51], v[192:193], v[74:75], v[80:81] neg_lo:[0,0,1] neg_hi:[0,0,1]
	v_pk_fma_f32 v[52:53], v[192:193], v[78:79], v[84:85] neg_lo:[0,0,1] neg_hi:[0,0,1]
	v_pk_add_f32 v[18:19], v[18:19], v[24:25]
	v_pk_add_f32 v[20:21], v[20:21], v[22:23]
	v_pk_add_f32 v[14:15], v[14:15], v[26:27]
	v_pk_add_f32 v[16:17], v[16:17], v[28:29]
	v_pk_add_f32 v[10:11], v[10:11], v[30:31]
	v_pk_add_f32 v[12:13], v[12:13], v[32:33]
	v_pk_add_f32 v[6:7], v[6:7], v[34:35]
	v_pk_add_f32 v[8:9], v[8:9], v[36:37]
	v_pk_add_f32 v[196:197], v[196:197], v[196:197] op_sel:[0,1] op_sel_hi:[0,1] neg_lo:[0,1] neg_hi:[0,1]
	v_pk_mul_f32 v[150:151], v[190:191], v[150:151]
	v_pk_mul_f32 v[154:155], v[190:191], v[154:155]
	v_pk_mul_f32 v[158:159], v[190:191], v[158:159]
	v_pk_mul_f32 v[162:163], v[190:191], v[162:163]
	v_pk_mul_f32 v[166:167], v[190:191], v[166:167]
	v_pk_mul_f32 v[170:171], v[190:191], v[170:171]
	v_pk_mul_f32 v[174:175], v[190:191], v[174:175]
	v_pk_mul_f32 v[178:179], v[190:191], v[178:179]
	v_pk_fma_f32 v[54:55], v[82:83], v[194:195], v[88:89] neg_lo:[0,0,1] neg_hi:[0,0,1]
	v_pk_fma_f32 v[56:57], v[194:195], v[86:87], v[92:93] neg_lo:[0,0,1] neg_hi:[0,0,1]
	v_pk_fma_f32 v[58:59], v[194:195], v[90:91], v[96:97] neg_lo:[0,0,1] neg_hi:[0,0,1]
	v_pk_fma_f32 v[60:61], v[194:195], v[94:95], v[100:101] neg_lo:[0,0,1] neg_hi:[0,0,1]
	v_pk_fma_f32 v[62:63], v[194:195], v[98:99], v[104:105] neg_lo:[0,0,1] neg_hi:[0,0,1]
	v_pk_fma_f32 v[64:65], v[194:195], v[102:103], v[108:109] neg_lo:[0,0,1] neg_hi:[0,0,1]
	v_pk_fma_f32 v[66:67], v[194:195], v[106:107], v[112:113] neg_lo:[0,0,1] neg_hi:[0,0,1]
	v_pk_fma_f32 v[68:69], v[194:195], v[110:111], v[146:147] neg_lo:[0,0,1] neg_hi:[0,0,1]
	v_pk_add_f32 v[18:19], v[18:19], v[38:39]
	v_pk_add_f32 v[20:21], v[20:21], v[40:41]
	v_pk_add_f32 v[14:15], v[14:15], v[42:43]
	v_pk_add_f32 v[16:17], v[16:17], v[44:45]
	v_pk_add_f32 v[10:11], v[10:11], v[46:47]
	v_pk_add_f32 v[12:13], v[12:13], v[48:49]
	v_pk_add_f32 v[6:7], v[6:7], v[50:51]
	v_pk_add_f32 v[8:9], v[8:9], v[52:53]
	s_add_i32 s24, s24, 32
	v_pk_fma_f32 v[70:71], v[144:145], v[196:197], v[150:151] neg_lo:[0,0,1] neg_hi:[0,0,1]
	v_pk_fma_f32 v[72:73], v[196:197], v[148:149], v[154:155] neg_lo:[0,0,1] neg_hi:[0,0,1]
	v_pk_fma_f32 v[74:75], v[196:197], v[152:153], v[158:159] neg_lo:[0,0,1] neg_hi:[0,0,1]
	v_pk_fma_f32 v[76:77], v[196:197], v[156:157], v[162:163] neg_lo:[0,0,1] neg_hi:[0,0,1]
	v_pk_fma_f32 v[78:79], v[196:197], v[160:161], v[166:167] neg_lo:[0,0,1] neg_hi:[0,0,1]
	v_pk_fma_f32 v[80:81], v[196:197], v[164:165], v[170:171] neg_lo:[0,0,1] neg_hi:[0,0,1]
	v_pk_fma_f32 v[82:83], v[196:197], v[168:169], v[174:175] neg_lo:[0,0,1] neg_hi:[0,0,1]
	v_pk_fma_f32 v[84:85], v[196:197], v[172:173], v[178:179] neg_lo:[0,0,1] neg_hi:[0,0,1]
	v_pk_add_f32 v[18:19], v[18:19], v[54:55]
	v_pk_add_f32 v[20:21], v[20:21], v[56:57]
	v_pk_add_f32 v[14:15], v[14:15], v[58:59]
	v_pk_add_f32 v[16:17], v[16:17], v[60:61]
	v_pk_add_f32 v[10:11], v[10:11], v[62:63]
	v_pk_add_f32 v[12:13], v[12:13], v[64:65]
	v_pk_add_f32 v[6:7], v[6:7], v[66:67]
	v_pk_add_f32 v[8:9], v[8:9], v[68:69]
	v_add_u32_e32 v122, 0x200, v122
	s_cmpk_eq_i32 s24, 0x200
	v_pk_add_f32 v[18:19], v[18:19], v[70:71]
	v_pk_add_f32 v[20:21], v[20:21], v[72:73]
	v_pk_add_f32 v[14:15], v[14:15], v[74:75]
	v_pk_add_f32 v[16:17], v[16:17], v[76:77]
	v_pk_add_f32 v[10:11], v[10:11], v[78:79]
	v_pk_add_f32 v[12:13], v[12:13], v[80:81]
	v_pk_add_f32 v[6:7], v[6:7], v[82:83]
	v_pk_add_f32 v[8:9], v[8:9], v[84:85]
	s_cbranch_scc0 .LBB0_346
; __device__ __forceinline__ bfr f2bf(float f) { return (bfr)(pk2(f, f) & 0xffffu); }
; __device__ __forceinline__ void prep_s5(const PRef& P, int slot, bfr* __restrict__ Gall, bfr* __restrict__ W2all, float2* __restrict__ lam16) {
;     ...
;       for (int i = 0; i < 16; ++i) kt[(dir * 16 + j) * 256 + o * 16 + i] = a16[i]; }
;     __syncthreads();
;     bfr* Gg = Gall + (long)g * 65536;
;     for (int e = tid; e < 65536; e += 512) { int n = e >> 8, k = e & 255; int dir = n >> 7, ri = (n >> 6) & 1, p = n & 63, s = k >> 4, i = k & 15;
;       int ex = dir == 0 ? 15 - s : s; float2 w = pw[(dir * 17 + ex) * 64 + p], b = bb[(dir * 64 + p) * 16 + i];
;       Gg[e] = f2bf(ri == 0 ? (w.x * b.x - w.y * b.y) : (w.x * b.y + w.y * b.x)); }
;     bfr* Wg = W2all + (long)g * 131072;
;     for (int e = tid; e < 131072; e += 512) { int n2 = e >> 9, k = e & 511; int t = n2 >> 4, o = n2 & 15; float val;
	ds_write_b128 v141, v[18:21] offset:50176
	ds_write_b128 v141, v[14:17] offset:50192
	ds_write_b128 v141, v[10:13] offset:50208
	ds_write_b128 v141, v[6:9] offset:50224
	s_waitcnt lgkmcnt(0)
	s_barrier
	s_and_saveexec_b64 s[26:27], s[10:11]
	s_cbranch_execz .LBB0_350
	s_lshl_b64 s[24:25], s[28:29], 17
	s_add_u32 s24, s24, s90
	s_addc_u32 s25, s25, 0
	v_lshl_add_u64 v[6:7], v[118:119], 0, s[24:25]
	s_mov_b64 s[60:61], 0
	v_add_u32_e32 v8, s32, v114
.LBB0_349:
	v_lshrrev_b32_e32 v11, 4, v8
	v_bfe_u32 v12, v8, 4, 4
	v_bitop3_b32 v11, v11, 15, v11 bitop3:0xc
	v_cmp_gt_u32_e64 s[24:25], s80, v8
	v_ashrrev_i32_e32 v9, 15, v8
	v_bfe_u32 v10, v8, 8, 6
	v_cndmask_b32_e64 v11, v12, v11, s[24:25]
	v_lshlrev_b32_e32 v13, 3, v127
	v_lshlrev_b32_e32 v15, 3, v10
	v_lshlrev_b32_e32 v17, 13, v9
	v_lshlrev_b32_e32 v10, 7, v10
	v_mad_i32_i24 v9, v9, 17, v11
	v_or3_b32 v12, v17, v10, v13
	v_lshl_or_b32 v9, v9, 9, v15
	ds_read_b64 v[10:11], v9
	ds_read_b64 v[12:13], v12 offset:17408
	v_add_u32_e32 v14, 0x200, v8
	v_and_b32_e32 v16, 0x4000, v8
	v_cmp_lt_i32_e32 vcc, s95, v8
	v_mov_b32_e32 v8, v14
	s_waitcnt lgkmcnt(0)
	v_pk_mul_f32 v[14:15], v[10:11], v[12:13]
	v_pk_mul_f32 v[10:11], v[10:11], v[12:13] op_sel:[1,0] op_sel_hi:[0,1]
	s_or_b64 s[60:61], vcc, s[60:61]
	v_sub_f32_e32 v9, v14, v15
	v_add_f32_e32 v10, v10, v11
	v_cmp_eq_u32_e32 vcc, 0, v16
	s_nop 1
	v_cndmask_b32_e32 v9, v10, v9, vcc
	v_cvt_pk_bf16_f32 v9, v9, v9
	global_store_short v[6:7], v9, off
	v_lshl_add_u64 v[6:7], v[6:7], 0, s[58:59]
	s_andn2_b64 exec, exec, s[60:61]
	s_cbranch_execnz .LBB0_349
.LBB0_350:
	s_or_b64 exec, exec, s[26:27]
	s_and_saveexec_b64 s[24:25], s[12:13]
	s_cbranch_execz .LBB0_148
	s_lshl_b64 s[26:27], s[28:29], 18
	s_add_u32 s26, s26, s90
	s_addc_u32 s27, s27, 0
	s_add_u32 s26, s26, s90
	s_addc_u32 s27, s27, 0
	v_lshl_add_u64 v[6:7], v[120:121], 0, s[26:27]
	s_mov_b64 s[26:27], 0
	v_add_u32_e32 v8, s90, v114
	s_branch .LBB0_354

; __device__ __forceinline__ bfr f2bf(float f) { return (bfr)(pk2(f, f) & 0xffffu); }
; __device__ __forceinline__ void prep_s5(const PRef& P, int slot, bfr* __restrict__ Gall, bfr* __restrict__ W2all, float2* __restrict__ lam16) {
;     ...
;     for (int e = tid; e < 131072; e += 512) { int n2 = e >> 9, k = e & 511; int t = n2 >> 4, o = n2 & 15; float val;
;       if (k < 256) { int s = k >> 4, i = k & 15; val = 0.f; if (t >= s) val += kt[(0 * 16 + (t - s)) * 256 + o * 16 + i]; if (s >= t) val += kt[(1 * 16 + (s - t)) * 256 + o * 16 + i]; }
;       else { int dir = (k - 256) >> 7, ri = (k >> 6) & 1, p = k & 63; int ex = dir == 0 ? t + 1 : 16 - t;
;         float2 c = cc[(dir * 16 + o) * 64 + p], w = pw[(dir * 17 + ex) * 64 + p]; val = ri == 0 ? (c.x * w.x - c.y * w.y) : -(c.x * w.y + c.y * w.x); }
;       Wg[e] = f2bf(val); }
.LBB0_353:
	s_or_b64 exec, exec, s[60:61]
	v_cvt_pk_bf16_f32 v9, v9, v9
	global_store_short v[6:7], v9, off
	v_add_u32_e32 v9, 0x200, v8
	v_cmp_lt_i32_e32 vcc, s91, v8
	v_lshl_add_u64 v[6:7], v[6:7], 0, s[58:59]
	s_or_b64 s[26:27], vcc, s[26:27]
	v_mov_b32_e32 v8, v9
	s_andn2_b64 exec, exec, s[26:27]
	s_cbranch_execz .LBB0_148
